# scan workgroup decode remapped so the four row-quarter workgroups (and all roles) of a head run on one XCD and share its L2 for the staged y/prep reads
# speedup vs baseline: 1.0312x; 1.0053x over previous
.LBB0_2822:
	s_or_b64 exec, exec, s[4:5]
	v_readlane_b32 s2, v255, 0
	s_waitcnt lgkmcnt(0)
	s_barrier
	s_cmpk_gt_i32 s2, 0xbf
	s_cbranch_scc1 .LBB0_2885
	s_mov_b32 s6, s64
	s_mov_b32 s2, s3
	s_mov_b32 s4, -1
	v_readlane_b32 s7, v255, 0
	s_nop 3
	s_and_b32 s42, s7, 7
	s_lshl_b32 s42, s42, 2
	s_bfe_u32 s43, s7, 0x20003
	s_and_b32 s7, s7, 0xe0
	s_or_b32 s7, s7, s42
	s_or_b32 s7, s7, s43
	s_load_dwordx2 s[86:87], s[0:1], s78
	s_waitcnt lgkmcnt(0)
	s_load_dwordx2 s[14:15], s[0:1], s78
	s_waitcnt lgkmcnt(0)
	s_ashr_i32 s18, s7, 6
	s_lshr_b32 s42, s7, 2
	s_and_b32 s43, s7, 3
	s_load_dwordx2 s[20:21], s[0:1], s78
	s_waitcnt lgkmcnt(0)
	s_cmp_lt_u32 s7, 64
	s_load_dwordx2 s[12:13], s[0:1], s78
	s_waitcnt lgkmcnt(0)
	v_mbcnt_lo_u32_b32 v0, s4, 0
	s_cselect_b64 s[16:17], -1, 0
	s_load_dwordx2 s[84:85], s[0:1], s78
	s_waitcnt lgkmcnt(0)
	v_mbcnt_hi_u32_b32 v158, s4, v0
	s_and_b64 s[4:5], s[16:17], exec
	s_load_dwordx2 s[88:89], s[0:1], s78
	s_waitcnt lgkmcnt(0)
	s_movk_i32 s4, 0x201
	s_cselect_b32 s50, 0, 0x101
	s_cselect_b32 s51, 0x101, s4
	s_mov_b64 s[4:5], -1
	s_cmp_gt_i32 s2, 3
	v_and_b32_e32 v159, 15, v158
	s_cbranch_scc0 .LBB0_2876
	s_add_u32 s94, s20, 0x7200000
	s_addc_u32 s95, s21, 0
	s_add_u32 s96, s12, 0x15600000
	s_addc_u32 s97, s13, 0
	s_add_u32 s92, s84, 0x1d800000
	s_addc_u32 s93, s85, 0
	s_bitcmp0_b32 s7, 5
	s_movk_i32 s4, 0x41e0
	s_cselect_b32 s10, 0xe0, s4
	s_lshl_b32 s4, s2, 6
	s_addk_i32 s4, 0xff00
	v_add_u32_e32 v148, s4, v158
	s_lshl_b32 s4, s42, 6
	s_and_b32 s19, s4, 0x1c0
	s_mov_b32 s4, 56
	s_load_dwordx2 s[4:5], s[0:1], s4
	s_waitcnt lgkmcnt(0)
	s_mul_i32 s8, s6, 0x1c80
	s_waitcnt vmcnt(0)
	v_lshl_or_b32 v26, v159, 2, s19
	s_mul_hi_i32 s7, s6, 0x1c80
	s_add_u32 s4, s4, s8
	s_addc_u32 s5, s5, s7
	v_lshlrev_b32_e32 v0, 2, v26
	v_lshl_add_u64 v[6:7], s[4:5], 0, v[0:1]
	v_add_co_u32_e32 v10, vcc, s83, v6
	s_lshl_b32 s8, s6, 9
	s_nop 0
	v_addc_co_u32_e32 v11, vcc, 0, v7, vcc
	global_load_dwordx4 v[2:5], v0, s[4:5] offset:2048
	global_load_dwordx4 v[6:9], v0, s[4:5]
	s_nop 0
	global_load_dwordx4 v[10:13], v[10:11], off
	s_movk_i32 s4, 0x80
	s_ashr_i32 s9, s8, 31
	s_load_dwordx2 s[4:5], s[0:1], s4
	s_waitcnt lgkmcnt(0)
	s_lshl_b64 s[8:9], s[8:9], 2
	s_add_u32 s4, s4, s8
	s_addc_u32 s5, s5, s9
	global_load_dwordx4 v[14:17], v0, s[4:5]
	s_movk_i32 s4, 0x88
	v_ashrrev_i32_e32 v104, 4, v148
	s_load_dwordx2 s[4:5], s[0:1], s4
	s_waitcnt lgkmcnt(0)
	s_mov_b32 s11, s45
	s_add_u32 s4, s4, s8
	v_ashrrev_i32_e32 v105, 31, v104
	s_addc_u32 s5, s5, s9
	s_lshl_b32 s90, s50, 5
	s_mov_b32 s91, s45
	v_lshl_add_u64 v[38:39], s[10:11], 0, v[104:105]
	v_lshl_add_u64 v[22:23], v[38:39], 0, s[90:91]
	v_mov_b64_e32 v[24:25], s[94:95]
	global_load_dwordx4 v[18:21], v0, s[4:5]
	v_mad_i64_i32 v[24:25], s[4:5], v22, s27, v[24:25]
	v_lshlrev_b32_e32 v0, 1, v26
	v_lshl_add_u64 v[24:25], v[24:25], 0, v[0:1]
	s_movk_i32 s4, 0xf000
	v_add_co_u32_e32 v26, vcc, s4, v24
	s_cmp_gt_i32 s6, 0
	s_nop 0
	v_addc_co_u32_e32 v27, vcc, -1, v25, vcc
	global_load_dwordx2 v[60:61], v[24:25], off
	global_load_dwordx2 v[58:59], v[26:27], off offset:-3072
	global_load_dwordx2 v[56:57], v[24:25], off offset:1024
	global_load_dwordx2 v[42:43], v[24:25], off offset:2048
	global_load_dwordx2 v[54:55], v[26:27], off offset:-2048
	global_load_dwordx2 v[46:47], v[26:27], off offset:-1024
	v_lshlrev_b64 v[24:25], 12, v[22:23]
	v_lshl_add_u64 v[24:25], s[96:97], 0, v[24:25]
	v_lshl_add_u64 v[24:25], v[24:25], 0, v[0:1]
	global_load_dwordx2 v[62:63], v[24:25], off
	global_load_dwordx2 v[52:53], v[24:25], off offset:1024
	s_cselect_b64 s[4:5], -1, 0
	s_cmp_lt_i32 s6, 1
	s_cbranch_scc1 .LBB0_2826
	v_lshlrev_b64 v[22:23], 10, v[22:23]
	v_lshl_add_u64 v[22:23], s[92:93], 0, v[22:23]
	v_lshl_add_u64 v[22:23], v[22:23], 0, v[0:1]
	global_load_dwordx2 v[44:45], v[24:25], off offset:3072
	global_load_dwordx2 v[48:49], v[22:23], off
	s_branch .LBB0_2827
